# entry converts only layer-0 in_proj weights on blocks 288+; layer-0 out_proj weights converted by blocks 128-255 at phase 3 start
# baseline (speedup 1.0000x reference)
.Lcc_skip:
	s_mov_b32 s12, s2
	s_movk_i32 s22, 0x2ff
	s_cmp_eq_u32 s3, 0x200
	s_cbranch_scc0 .Lwc_loop
	s_movk_i32 s22, 0xdf
	s_sub_u32 s12, s2, 0x120

.Ldc3_conv:
	s_cmpk_gt_i32 s55, 0xff
	s_cbranch_scc1 .LBB0_263
	s_cmp_lg_u32 s92, 0x200
	s_cbranch_scc1 .LBB0_263
	v_readlane_b32 s0, v253, 4
	v_readlane_b32 s1, v253, 5
	s_nop 1
	s_sub_u32 s0, s0, 0x228
	s_subb_u32 s1, s1, 0
	s_load_dwordx2 s[16:17], s[0:1], 0xb0
	s_add_u32 s12, s55, 0x60
	v_lshrrev_b32_e32 v2, 6, v250
	v_and_b32_e32 v3, 63, v250
	v_lshlrev_b32_e32 v2, 12, v2
	v_lshl_or_b32 v2, v3, 4, v2
	v_and_b32_e32 v3, 31, v250
	v_lshrrev_b32_e32 v4, 5, v250
	v_lshlrev_b32_e32 v3, 4, v3
	s_lshr_b32 s13, s12, 4
	s_and_b32 s14, s12, 15
	s_movk_i32 s15, 0x1000
	s_sub_u32 s18, s13, 14
	s_waitcnt lgkmcnt(0)
	s_lshl_b32 s19, s14, 6
	s_mul_i32 s19, s19, s15
	s_lshl_b32 s20, s18, 9
	s_add_u32 s19, s19, s20
	s_add_u32 s16, s16, s19
	s_addc_u32 s17, s17, 0
	s_lshl_b32 s20, s15, 3
	v_mul_lo_u32 v5, v4, s20
	v_add_u32_e32 v5, v5, v3
	global_load_dwordx4 v[8:11], v5, s[16:17]
	s_add_u32 s16, s16, s15
	s_addc_u32 s17, s17, 0
	global_load_dwordx4 v[12:15], v5, s[16:17]
	s_add_u32 s16, s16, s15
	s_addc_u32 s17, s17, 0
	global_load_dwordx4 v[16:19], v5, s[16:17]
	s_add_u32 s16, s16, s15
	s_addc_u32 s17, s17, 0
	global_load_dwordx4 v[20:23], v5, s[16:17]
	s_add_u32 s16, s16, s15
	s_addc_u32 s17, s17, 0
	global_load_dwordx4 v[24:27], v5, s[16:17]
	s_add_u32 s16, s16, s15
	s_addc_u32 s17, s17, 0
	global_load_dwordx4 v[28:31], v5, s[16:17]
	s_add_u32 s16, s16, s15
	s_addc_u32 s17, s17, 0
	global_load_dwordx4 v[32:35], v5, s[16:17]
	s_add_u32 s16, s16, s15
	s_addc_u32 s17, s17, 0
	global_load_dwordx4 v[36:39], v5, s[16:17]
	s_lshl_b32 s19, s12, 14
	s_add_u32 s20, s100, s19
	s_addc_u32 s21, s101, 0
	s_waitcnt vmcnt(0)
	v_cvt_pk_bf16_f32 v40, v8, v12
	v_cvt_pk_bf16_f32 v41, v16, v20
	v_cvt_pk_bf16_f32 v42, v24, v28
	v_cvt_pk_bf16_f32 v43, v32, v36
	global_store_dwordx4 v2, v[40:43], s[20:21]
	v_cvt_pk_bf16_f32 v44, v9, v13
	v_cvt_pk_bf16_f32 v45, v17, v21
	v_cvt_pk_bf16_f32 v46, v25, v29
	v_cvt_pk_bf16_f32 v47, v33, v37
	global_store_dwordx4 v2, v[44:47], s[20:21] offset:1024
	v_cvt_pk_bf16_f32 v48, v10, v14
	v_cvt_pk_bf16_f32 v49, v18, v22
	v_cvt_pk_bf16_f32 v50, v26, v30
	v_cvt_pk_bf16_f32 v51, v34, v38
	global_store_dwordx4 v2, v[48:51], s[20:21] offset:2048
	v_cvt_pk_bf16_f32 v52, v11, v15
	v_cvt_pk_bf16_f32 v53, v19, v23
	v_cvt_pk_bf16_f32 v54, v27, v31
	v_cvt_pk_bf16_f32 v55, v35, v39
	global_store_dwordx4 v2, v[52:55], s[20:21] offset:3072
